# barrier leader: L2 write-back issued before the L1 invalidate and only the write-back is awaited before the cross-XCD arrival (invalidate completes in the shadow of the arrival atomic)
# speedup vs baseline: 1.0105x; 1.0079x over previous
; __device__ __forceinline__ unsigned xb_add(unsigned* p, unsigned v) { return __hip_atomic_fetch_add(p, v, __ATOMIC_RELAXED, __HIP_MEMORY_SCOPE_AGENT); }
; __device__ __forceinline__ void xcd_barrier(const XcdBarrier& b, int xtid) {
;     ...
;         if (old + 1u == (gen + 1u) * nloc) {
;             __builtin_amdgcn_fence(__ATOMIC_RELEASE, "agent");
;             asm volatile("s_waitcnt vmcnt(0)" ::: "memory");
;             const unsigned og = xb_add(&bar[XB_TOP], 1u);
.LBB0_137:
	s_andn2_saveexec_b64 s[6:7], s[6:7]
	s_cbranch_execz .LBB0_157
	s_mov_b64 s[6:7], exec
	buffer_wbl2 sc1
	buffer_inv sc1
	s_waitcnt lgkmcnt(0)
	s_waitcnt vmcnt(1)
	v_mbcnt_lo_u32_b32 v1, s6, 0
	v_mbcnt_hi_u32_b32 v1, s7, v1
	v_cmp_eq_u32_e32 vcc, 0, v1
	s_and_saveexec_b64 s[8:9], vcc
	s_cbranch_execz .LBB0_140
	s_bcnt1_i32_b64 s6, s[6:7]
	v_mov_b32_e32 v2, s6
	v_readlane_b32 s6, v253, 14
	v_readlane_b32 s7, v253, 15
	s_nop 4
	global_atomic_add v2, v161, v2, s[6:7] sc0

; __device__ __forceinline__ unsigned xb_add(unsigned* p, unsigned v) { return __hip_atomic_fetch_add(p, v, __ATOMIC_RELAXED, __HIP_MEMORY_SCOPE_AGENT); }
; __device__ __forceinline__ void xcd_barrier(const XcdBarrier& b, int xtid) {
;     ...
;         if (old + 1u == (gen + 1u) * nloc) {
;             __builtin_amdgcn_fence(__ATOMIC_RELEASE, "agent");
;             asm volatile("s_waitcnt vmcnt(0)" ::: "memory");
;             const unsigned og = xb_add(&bar[XB_TOP], 1u);
.LBB0_255:
	s_andn2_saveexec_b64 s[8:9], s[8:9]
	s_cbranch_execz .LBB0_275
	s_mov_b64 s[8:9], exec
	buffer_wbl2 sc1
	buffer_inv sc1
	s_waitcnt lgkmcnt(0)
	s_waitcnt vmcnt(1)
	v_mbcnt_lo_u32_b32 v1, s8, 0
	v_mbcnt_hi_u32_b32 v1, s9, v1
	v_cmp_eq_u32_e32 vcc, 0, v1
	s_and_saveexec_b64 s[10:11], vcc
	s_cbranch_execz .LBB0_258
	s_bcnt1_i32_b64 s8, s[8:9]
	v_mov_b32_e32 v2, s8
	v_readlane_b32 s8, v253, 14
	v_readlane_b32 s9, v253, 15
	s_nop 4
	global_atomic_add v2, v161, v2, s[8:9] sc0

; __device__ __forceinline__ unsigned xb_add(unsigned* p, unsigned v) { return __hip_atomic_fetch_add(p, v, __ATOMIC_RELAXED, __HIP_MEMORY_SCOPE_AGENT); }
; __device__ __forceinline__ void xcd_barrier(const XcdBarrier& b, int xtid) {
;     ...
;         if (old + 1u == (gen + 1u) * nloc) {
;             __builtin_amdgcn_fence(__ATOMIC_RELEASE, "agent");
;             asm volatile("s_waitcnt vmcnt(0)" ::: "memory");
;             const unsigned og = xb_add(&bar[XB_TOP], 1u);
.LBB0_458:
	s_andn2_saveexec_b64 s[10:11], s[10:11]
	s_cbranch_execz .LBB0_478
	s_mov_b64 s[10:11], exec
	buffer_wbl2 sc1
	buffer_inv sc1
	s_waitcnt lgkmcnt(0)
	s_waitcnt vmcnt(1)
	v_mbcnt_lo_u32_b32 v1, s10, 0
	v_mbcnt_hi_u32_b32 v1, s11, v1
	v_cmp_eq_u32_e32 vcc, 0, v1
	s_and_saveexec_b64 s[12:13], vcc
	s_cbranch_execz .LBB0_461
	s_bcnt1_i32_b64 s10, s[10:11]
	v_mov_b32_e32 v2, s10
	v_readlane_b32 s10, v253, 14
	v_readlane_b32 s11, v253, 15
	s_nop 4
	global_atomic_add v2, v161, v2, s[10:11] sc0

; __device__ __forceinline__ unsigned xb_add(unsigned* p, unsigned v) { return __hip_atomic_fetch_add(p, v, __ATOMIC_RELAXED, __HIP_MEMORY_SCOPE_AGENT); }
; __device__ __forceinline__ void xcd_barrier(const XcdBarrier& b, int xtid) {
;     ...
;         if (old + 1u == (gen + 1u) * nloc) {
;             __builtin_amdgcn_fence(__ATOMIC_RELEASE, "agent");
;             asm volatile("s_waitcnt vmcnt(0)" ::: "memory");
;             const unsigned og = xb_add(&bar[XB_TOP], 1u);
.LBB0_524:
	s_andn2_saveexec_b64 s[12:13], s[12:13]
	s_cbranch_execz .LBB0_544
	s_mov_b64 s[12:13], exec
	buffer_wbl2 sc1
	buffer_inv sc1
	s_waitcnt lgkmcnt(0)
	s_waitcnt vmcnt(1)
	v_mbcnt_lo_u32_b32 v1, s12, 0
	v_mbcnt_hi_u32_b32 v1, s13, v1
	v_cmp_eq_u32_e32 vcc, 0, v1
	s_and_saveexec_b64 s[14:15], vcc
	s_cbranch_execz .LBB0_527
	s_bcnt1_i32_b64 s12, s[12:13]
	v_mov_b32_e32 v2, s12
	v_readlane_b32 s12, v253, 14
	v_readlane_b32 s13, v253, 15
	s_nop 4
	global_atomic_add v2, v161, v2, s[12:13] sc0

; __device__ __forceinline__ unsigned xb_add(unsigned* p, unsigned v) { return __hip_atomic_fetch_add(p, v, __ATOMIC_RELAXED, __HIP_MEMORY_SCOPE_AGENT); }
; __device__ __forceinline__ void xcd_barrier(const XcdBarrier& b, int xtid) {
;     ...
;         if (old + 1u == (gen + 1u) * nloc) {
;             __builtin_amdgcn_fence(__ATOMIC_RELEASE, "agent");
;             asm volatile("s_waitcnt vmcnt(0)" ::: "memory");
;             const unsigned og = xb_add(&bar[XB_TOP], 1u);
.LBB0_1092:
	s_mov_b64 s[6:7], exec
	buffer_wbl2 sc1
	buffer_inv sc1
	s_waitcnt lgkmcnt(0)
	s_waitcnt vmcnt(1)
	v_mbcnt_lo_u32_b32 v1, s6, 0
	v_mbcnt_hi_u32_b32 v1, s7, v1
	v_cmp_eq_u32_e32 vcc, 0, v1
	s_and_saveexec_b64 s[8:9], vcc
	s_cbranch_execz .LBB0_1094
	s_bcnt1_i32_b64 s6, s[6:7]
	v_mov_b32_e32 v2, s6
	v_readlane_b32 s6, v253, 14
	v_readlane_b32 s7, v253, 15
	s_nop 4
	global_atomic_add v2, v161, v2, s[6:7] sc0
